# speedup vs baseline: 1.0277x; 1.0057x over previous
; __device__ __forceinline__ void attn_item(const int WV, const Params& P, int bh, int qb) {
;     ...
;       float mx = -INFINITY;
; #pragma unroll
;       for (int kb = 0; kb < 2; ++kb)
; #pragma unroll
;         for (int i = 0; i < 16; ++i) mx = fmaxf(mx, st[kb][i]);
;       {
;         auto rr = __builtin_amdgcn_permlane32_swap(__float_as_uint(mx), __float_as_uint(mx), false, false);
;         mx = fmaxf(__uint_as_float(rr[0]), __uint_as_float(rr[1]));
;       }
;       const float mn = fmaxf(m, mx);
;       const float alpha = __builtin_amdgcn_exp2f(m - mn);
;       m = mn;
;       float ps = 0.f;
;       bf16x8 pb[4];
; #pragma unroll
;       for (int kb = 0; kb < 2; ++kb)
; #pragma unroll
;         for (int i = 0; i < 16; i += 2) {
;           float p0 = __builtin_amdgcn_exp2f(st[kb][i] - mn), p1 = __builtin_amdgcn_exp2f(st[kb][i + 1] - mn);
;           ps += p0 + p1;
;           unsigned pk = pack2bf(p0, p1);
;           pb[kb * 2 + (i >> 3)][i & 7] = (short)(pk & 0xffff);
;           pb[kb * 2 + (i >> 3)][(i & 7) + 1] = (short)(pk >> 16);
;         }
;       l = l * alpha + ps;
; #pragma unroll
;       for (int i = 0; i < 16; ++i) { ot[0][i] *= alpha; ot[1][i] *= alpha; }
;       const char* vb = cur + 64 * KP;
; #pragma unroll
;       for (int db = 0; db < 2; ++db)
; #pragma unroll
;         for (int s = 0; s < 4; ++s) {
;           const char* rp = vb + (db * 32 + n) * KP + (16 * s + 4 * hf) * 2;
;           typedef __attribute__((ext_vector_type(4))) short s16x4;
;           s16x4 lo = *(const s16x4*)rp, hi = *(const s16x4*)(rp + 16);
;           bf16x8 a;
;           a[0] = lo[0]; a[1] = lo[1]; a[2] = lo[2]; a[3] = lo[3]; a[4] = hi[0]; a[5] = hi[1]; a[6] = hi[2]; a[7] = hi[3];
;           ot[db] = __builtin_amdgcn_mfma_f32_32x32x16_bf16(a, pb[s], ot[db], 0, 0, 0);
;         }
.LBB0_389:
	s_or_b64 exec, exec, s[20:21]
	v_add3_u32 v232, s34, v134, v128
	v_add_u32_e32 v233, 0x2000, v232
	v_add_u32_e32 v234, 0x3000, v232
	ds_read2_b64 v[200:203], v233 offset0:128 offset1:130
	ds_read2_b64 v[204:207], v234 offset0:192 offset1:194
	ds_read2_b64 v[208:211], v233 offset0:132 offset1:134
	ds_read2_b64 v[212:215], v234 offset0:196 offset1:198
	ds_read2_b64 v[216:219], v233 offset0:136 offset1:138
	ds_read2_b64 v[220:223], v234 offset0:200 offset1:202
	ds_read2_b64 v[224:227], v233 offset0:140 offset1:142
	ds_read2_b64 v[228:231], v234 offset0:204 offset1:206
	v_max3_f32 v0, v64, s76, v65
	v_max3_f32 v0, v0, v66, v67
	v_max3_f32 v0, v0, v68, v69
	v_max3_f32 v0, v0, v70, v71
	v_max3_f32 v0, v0, v72, v73
	v_max3_f32 v0, v0, v74, v75
	v_max3_f32 v0, v0, v76, v77
	v_max3_f32 v0, v0, v78, v79
	v_max3_f32 v0, v0, v48, v49
	v_max3_f32 v0, v0, v50, v51
	v_max3_f32 v0, v0, v52, v53
	v_max3_f32 v0, v0, v54, v55
	v_max3_f32 v0, v0, v56, v57
	v_max3_f32 v0, v0, v58, v59
	v_max3_f32 v0, v0, v60, v61
	v_max3_f32 v0, v0, v62, v63
	v_mov_b32_e32 v2, v0
	s_nop 1
	v_permlane32_swap_b32_e32 v0, v2
	v_max_f32_e32 v0, v0, v2
	v_sub_f32_e32 v2, v0, v137
	v_cmp_lt_f32_e32 vcc, 0x41400000, v2
	s_cbranch_vccz .Lat_noresc_a
	v_max_f32_e32 v138, v137, v0
	v_sub_f32_e32 v2, v137, v138
	v_exp_f32_e32 v2, v2
	v_mov_b32_e32 v137, v138
	s_nop 0
	v_mul_f32_e32 v136, v136, v2
	v_mul_f32_e32 v32, v32, v2
	v_mul_f32_e32 v33, v33, v2
	v_mul_f32_e32 v34, v34, v2
	v_mul_f32_e32 v35, v35, v2
	v_mul_f32_e32 v36, v36, v2
	v_mul_f32_e32 v37, v37, v2
	v_mul_f32_e32 v38, v38, v2
	v_mul_f32_e32 v39, v39, v2
	v_mul_f32_e32 v40, v40, v2
	v_mul_f32_e32 v41, v41, v2
	v_mul_f32_e32 v42, v42, v2
	v_mul_f32_e32 v43, v43, v2
	v_mul_f32_e32 v44, v44, v2
	v_mul_f32_e32 v45, v45, v2
	v_mul_f32_e32 v46, v46, v2
	v_mul_f32_e32 v47, v47, v2
	v_mul_f32_e32 v16, v16, v2
	v_mul_f32_e32 v17, v17, v2
	v_mul_f32_e32 v18, v18, v2
	v_mul_f32_e32 v19, v19, v2
	v_mul_f32_e32 v20, v20, v2
	v_mul_f32_e32 v21, v21, v2
	v_mul_f32_e32 v22, v22, v2
	v_mul_f32_e32 v23, v23, v2
	v_mul_f32_e32 v24, v24, v2
	v_mul_f32_e32 v25, v25, v2
	v_mul_f32_e32 v26, v26, v2
	v_mul_f32_e32 v27, v27, v2
	v_mul_f32_e32 v28, v28, v2
	v_mul_f32_e32 v29, v29, v2
	v_mul_f32_e32 v30, v30, v2
	v_mul_f32_e32 v31, v31, v2
.Lat_noresc_a:
	v_sub_f32_e32 v64, v64, v137
	v_sub_f32_e32 v65, v65, v137
	v_sub_f32_e32 v66, v66, v137
	v_sub_f32_e32 v67, v67, v137
	v_sub_f32_e32 v68, v68, v137
	v_sub_f32_e32 v69, v69, v137
	v_sub_f32_e32 v70, v70, v137
	v_sub_f32_e32 v71, v71, v137
	v_exp_f32_e32 v64, v64
	v_exp_f32_e32 v65, v65
	v_exp_f32_e32 v66, v66
	v_exp_f32_e32 v67, v67
	v_exp_f32_e32 v68, v68
	v_exp_f32_e32 v69, v69
	v_exp_f32_e32 v70, v70
	v_exp_f32_e32 v71, v71
	v_cvt_pk_bf16_f32 v2, v64, v65
	v_cvt_pk_bf16_f32 v3, v66, v67
	v_cvt_pk_bf16_f32 v4, v68, v69
	v_cvt_pk_bf16_f32 v5, v70, v71
	v_add_f32_e32 v14, v64, v65
	v_add_f32_e32 v15, v66, v67
	v_add_f32_e32 v0, v68, v69
	v_add_f32_e32 v240, v70, v71
	v_add_f32_e32 v14, v14, v15
	v_add_f32_e32 v0, v0, v240
	v_add_f32_e32 v14, v14, v0
	v_mov_b32_e32 v235, v14
	s_waitcnt lgkmcnt(6)
	v_mfma_f32_32x32x16_bf16 v[32:47], v[200:203], v[2:5], v[32:47]
	v_mfma_f32_32x32x16_bf16 v[16:31], v[204:207], v[2:5], v[16:31]
	v_sub_f32_e32 v72, v72, v137
	v_sub_f32_e32 v73, v73, v137
	v_sub_f32_e32 v74, v74, v137
	v_sub_f32_e32 v75, v75, v137
	v_sub_f32_e32 v76, v76, v137
	v_sub_f32_e32 v77, v77, v137
	v_sub_f32_e32 v78, v78, v137
	v_sub_f32_e32 v79, v79, v137
	v_exp_f32_e32 v72, v72
	v_exp_f32_e32 v73, v73
	v_exp_f32_e32 v74, v74
	v_exp_f32_e32 v75, v75
	v_exp_f32_e32 v76, v76
	v_exp_f32_e32 v77, v77
	v_exp_f32_e32 v78, v78
	v_exp_f32_e32 v79, v79
	v_cvt_pk_bf16_f32 v6, v72, v73
	v_cvt_pk_bf16_f32 v7, v74, v75
	v_cvt_pk_bf16_f32 v8, v76, v77
	v_cvt_pk_bf16_f32 v9, v78, v79
	v_add_f32_e32 v14, v72, v73
	v_add_f32_e32 v15, v74, v75
	v_add_f32_e32 v0, v76, v77
	v_add_f32_e32 v240, v78, v79
	v_add_f32_e32 v14, v14, v15
	v_add_f32_e32 v0, v0, v240
	v_add_f32_e32 v14, v14, v0
	v_add_f32_e32 v235, v235, v14
	s_waitcnt lgkmcnt(4)
	v_mfma_f32_32x32x16_bf16 v[32:47], v[208:211], v[6:9], v[32:47]
	v_mfma_f32_32x32x16_bf16 v[16:31], v[212:215], v[6:9], v[16:31]
	v_sub_f32_e32 v48, v48, v137
	v_sub_f32_e32 v49, v49, v137
	v_sub_f32_e32 v50, v50, v137
	v_sub_f32_e32 v51, v51, v137
	v_sub_f32_e32 v52, v52, v137
	v_sub_f32_e32 v53, v53, v137
	v_sub_f32_e32 v54, v54, v137
	v_sub_f32_e32 v55, v55, v137
	v_exp_f32_e32 v48, v48
	v_exp_f32_e32 v49, v49
	v_exp_f32_e32 v50, v50
	v_exp_f32_e32 v51, v51
	v_exp_f32_e32 v52, v52
	v_exp_f32_e32 v53, v53
	v_exp_f32_e32 v54, v54
	v_exp_f32_e32 v55, v55
	v_cvt_pk_bf16_f32 v10, v48, v49
	v_cvt_pk_bf16_f32 v11, v50, v51
	v_cvt_pk_bf16_f32 v12, v52, v53
	v_cvt_pk_bf16_f32 v13, v54, v55
	v_add_f32_e32 v14, v48, v49
	v_add_f32_e32 v15, v50, v51
	v_add_f32_e32 v0, v52, v53
	v_add_f32_e32 v240, v54, v55
	v_add_f32_e32 v14, v14, v15
	v_add_f32_e32 v0, v0, v240
	v_add_f32_e32 v14, v14, v0
	v_add_f32_e32 v235, v235, v14
	s_waitcnt lgkmcnt(2)
	v_mfma_f32_32x32x16_bf16 v[32:47], v[216:219], v[10:13], v[32:47]
	v_mfma_f32_32x32x16_bf16 v[16:31], v[220:223], v[10:13], v[16:31]
	v_sub_f32_e32 v56, v56, v137
	v_sub_f32_e32 v57, v57, v137
	v_sub_f32_e32 v58, v58, v137
	v_sub_f32_e32 v59, v59, v137
	v_sub_f32_e32 v60, v60, v137
	v_sub_f32_e32 v61, v61, v137
	v_sub_f32_e32 v62, v62, v137
	v_sub_f32_e32 v63, v63, v137
	v_exp_f32_e32 v56, v56
	v_exp_f32_e32 v57, v57
	v_exp_f32_e32 v58, v58
	v_exp_f32_e32 v59, v59
	v_exp_f32_e32 v60, v60
	v_exp_f32_e32 v61, v61
	v_exp_f32_e32 v62, v62
	v_exp_f32_e32 v63, v63
	v_cvt_pk_bf16_f32 v236, v56, v57
	v_cvt_pk_bf16_f32 v237, v58, v59
	v_cvt_pk_bf16_f32 v238, v60, v61
	v_cvt_pk_bf16_f32 v239, v62, v63
	v_add_f32_e32 v14, v56, v57
	v_add_f32_e32 v15, v58, v59
	v_add_f32_e32 v0, v60, v61
	v_add_f32_e32 v240, v62, v63
	v_add_f32_e32 v14, v14, v15
	v_add_f32_e32 v0, v0, v240
	v_add_f32_e32 v14, v14, v0
	v_add_f32_e32 v235, v235, v14
	s_waitcnt lgkmcnt(0)
	v_mfma_f32_32x32x16_bf16 v[32:47], v[224:227], v[236:239], v[32:47]
	v_mfma_f32_32x32x16_bf16 v[16:31], v[228:231], v[236:239], v[16:31]
	v_add_f32_e32 v136, v136, v235
